# forgetting-attention straight iteration unrolled over the three LDS slots: all LDS addresses are lane-constant register + immediate (no per-step VALU address adds)
# baseline (speedup 1.0000x reference)
.LBB0_683:
	s_and_b64 vcc, exec, s[74:75]
	s_mov_b32 s12, 0
	s_waitcnt lgkmcnt(0)
	s_barrier
	s_cbranch_vccnz .LBB0_735
	s_cmp_lg_u32 0x100, -1
	s_cselect_b32 s12, 0x100, 0
	s_add_i32 s14, s12, 0x3800
	s_addk_i32 s12, 0x2000
	v_add_u32_e32 v168, s12, v156
	s_lshl_b32 s12, s3, 2
	s_add_i32 s82, s82, s12
	s_mov_b32 s92, 0
	v_add_u32_e32 v167, s14, v156
	v_or_b32_e32 v169, 1, v157
	v_mov_b32_e32 v33, v32
	v_mov_b32_e32 v82, v32
	v_mov_b32_e32 v83, v32
	v_mov_b32_e32 v84, v32
	v_mov_b32_e32 v85, v32
	v_mov_b32_e32 v86, v32
	v_mov_b32_e32 v87, v32
	v_mov_b32_e32 v88, v32
	v_mov_b32_e32 v89, v32
	v_mov_b32_e32 v90, v32
	v_mov_b32_e32 v91, v32
	v_mov_b32_e32 v92, v32
	v_mov_b32_e32 v93, v32
	v_mov_b32_e32 v94, v32
	s_add_i32 s14, s76, 0x80
	s_sub_i32 s93, 0, s82
	s_mov_b32 s97, 0xa200
	s_movk_i32 s15, 0x5100
	s_mov_b32 s82, 3
	s_movk_i32 s83, 0xfe01
	v_mov_b32_e32 v95, v32
	v_lshl_add_u32 v182, v150, 1, v152
	v_readfirstlane_b32 s98, v157
	v_add_u32_e32 v183, v162, v163
	v_add_u32_e32 v206, v162, v164
	v_add_u32_e32 v207, v162, v165
	v_add_u32_e32 v245, v162, v166
.LBB0_685:
	s_add_i32 s12, s82, -1
	s_cmp_lt_i32 s12, s98
	s_cbranch_scc0 .LfB_generic
	s_add_i32 s12, s83, 0x202
	s_cmp_lt_i32 s12, s9
	s_cbranch_scc0 .LfB_generic
	s_cmp_eq_u32 s15, 0
	s_cbranch_scc1 .LfB_iter0
	s_cmp_eq_u32 s15, 0x5100
	s_cbranch_scc1 .LfB_iter1
	s_branch .LfB_iter2

.LfB_iter0:
	s_add_i32 s18, s14, 64
	s_ashr_i32 s19, s18, 31
	s_lshl_b64 s[20:21], s[18:19], 13
	s_add_u32 s15, s10, s20
	s_addc_u32 s21, s11, s21
	s_add_u32 s20, s15, s8
	s_addc_u32 s21, s21, 0
	s_add_u32 s20, s20, 0x1000
	s_addc_u32 s21, s21, 0
	global_load_dwordx4 v[136:139], v182, s[20:21] offset:1024
	s_and_saveexec_b64 s[20:21], s[6:7]
	s_cbranch_execz .LfB_688_0
	v_lshl_add_u64 v[2:3], s[18:19], 2, v[154:155]
	global_load_dwordx4 v[128:131], v[2:3], off
.LfB_688_0:
	s_or_b64 exec, exec, s[20:21]
	s_ashr_i32 s15, s14, 31
	s_lshl_b64 s[20:21], s[14:15], 13
	s_add_u32 s20, s95, s20
	s_addc_u32 s21, s96, s21
	s_add_u32 s20, s20, 0x1000
	s_addc_u32 s21, s21, 0
	global_load_dwordx4 v[132:135], v182, s[20:21] offset:2048
	s_waitcnt lgkmcnt(0)
	ds_read_b128 v[174:177], v148 offset:20960
	ds_read_b128 v[178:181], v148 offset:20928
	ds_read_b128 v[248:251], v148 offset:20896
	ds_read_b128 v[252:255], v148 offset:20864
	ds_read_b64_tr_b16 v[2:3], v167 offset:41472
	ds_read_b64_tr_b16 v[4:5], v167 offset:43008
	ds_read_b64_tr_b16 v[8:9], v167 offset:43072
	ds_read_b64_tr_b16 v[6:7], v167 offset:41536
	ds_read_b128 v[10:13], v183 offset:4352
	ds_read_b128 v[104:107], v206 offset:4352
	ds_read_b128 v[108:111], v207 offset:4352
	ds_read_b128 v[140:143], v245 offset:4352
	s_waitcnt lgkmcnt(11)
	v_sub_f32_e32 v49, v95, v177
	v_sub_f32_e32 v48, v94, v176
	v_sub_f32_e32 v47, v93, v175
	v_sub_f32_e32 v46, v92, v174
	s_waitcnt lgkmcnt(10)
	v_sub_f32_e32 v45, v91, v181
	v_sub_f32_e32 v44, v90, v180
	v_sub_f32_e32 v43, v89, v179
	v_sub_f32_e32 v42, v88, v178
	s_waitcnt lgkmcnt(9)
	v_sub_f32_e32 v41, v87, v251
	v_sub_f32_e32 v40, v86, v250
	v_sub_f32_e32 v39, v85, v249
	v_sub_f32_e32 v38, v84, v248
	s_waitcnt lgkmcnt(8)
	v_sub_f32_e32 v37, v83, v255
	v_sub_f32_e32 v36, v82, v254
	v_sub_f32_e32 v35, v33, v253
	v_sub_f32_e32 v34, v32, v252
	s_nop 1
	s_setprio 1
	s_waitcnt lgkmcnt(3)
	v_mfma_f32_32x32x16_bf16 v[34:49], v[10:13], v[120:123], v[34:49]
	v_exp_f32_e32 v14, v72
	v_exp_f32_e32 v15, v80
	s_waitcnt lgkmcnt(2)
	v_mfma_f32_32x32x16_bf16 v[34:49], v[104:107], v[112:115], v[34:49]
	ds_read_b64_tr_b16 v[10:11], v167 offset:44544
	ds_read_b64_tr_b16 v[12:13], v167 offset:46080
	ds_read_b64_tr_b16 v[104:105], v167 offset:44608
	ds_read_b64_tr_b16 v[106:107], v167 offset:46144
	v_mfma_f32_32x32x16_bf16 v[50:65], v[2:5], v[96:99], v[50:65]
	v_exp_f32_e32 v2, v66
	v_exp_f32_e32 v4, v67
	v_exp_f32_e32 v3, v74
	v_exp_f32_e32 v5, v75
	v_mfma_f32_32x32x16_bf16 v[16:31], v[6:9], v[96:99], v[16:31]
	v_exp_f32_e32 v6, v68
	v_exp_f32_e32 v8, v69
	v_exp_f32_e32 v7, v76
	v_exp_f32_e32 v9, v77
	s_waitcnt lgkmcnt(5)
	v_mfma_f32_32x32x16_bf16 v[34:49], v[108:111], v[116:119], v[34:49]
	s_waitcnt lgkmcnt(2)
	v_mfma_f32_32x32x16_bf16 v[50:65], v[10:13], v[100:103], v[50:65]
	v_exp_f32_e32 v10, v70
	v_exp_f32_e32 v12, v71
	v_exp_f32_e32 v11, v78
	v_exp_f32_e32 v13, v79
	s_waitcnt lgkmcnt(0)
	v_mfma_f32_32x32x16_bf16 v[16:31], v[104:107], v[100:103], v[16:31]
	v_exp_f32_e32 v102, v73
	v_exp_f32_e32 v103, v81
	v_add_f32_e32 v1, v14, v15
	v_add_f32_e32 v1, v1, v2
	v_add_f32_e32 v1, v1, v4
	v_add_f32_e32 v1, v1, v3
	v_add_f32_e32 v1, v1, v5
	v_add_f32_e32 v1, v1, v6
	v_add_f32_e32 v1, v1, v8
	v_add_f32_e32 v1, v1, v7
	v_add_f32_e32 v1, v1, v9
	v_add_f32_e32 v1, v1, v10
	v_add_f32_e32 v1, v1, v12
	v_add_f32_e32 v1, v1, v11
	v_add_f32_e32 v1, v1, v13
	v_add_f32_e32 v1, v1, v102
	v_add_f32_e32 v1, v1, v103
	v_add_f32_e32 v160, v160, v1
	v_mfma_f32_32x32x16_bf16 v[34:49], v[140:143], v[124:127], v[34:49]
	v_cvt_pk_bf16_f32 v98, v10, v12
	v_cvt_pk_bf16_f32 v96, v2, v4
	v_cvt_pk_bf16_f32 v97, v6, v8
	v_cvt_pk_bf16_f32 v99, v14, v102
	v_cvt_pk_bf16_f32 v100, v3, v5
	v_cvt_pk_bf16_f32 v101, v7, v9
	v_cvt_pk_bf16_f32 v102, v11, v13
	v_cvt_pk_bf16_f32 v103, v15, v103
	s_setprio 0
	s_waitcnt lgkmcnt(0)
	ds_read_b128 v[174:177], v148 offset:41568
	ds_read_b128 v[178:181], v148 offset:41536
	ds_read_b128 v[248:251], v148 offset:41504
	ds_read_b128 v[252:255], v148 offset:41472
	ds_read_b64_tr_b16 v[2:3], v168 offset:0
	ds_read_b64_tr_b16 v[4:5], v168 offset:1536
	ds_read_b64_tr_b16 v[8:9], v168 offset:1600
	ds_read_b64_tr_b16 v[6:7], v168 offset:64
	ds_read_b128 v[10:13], v183 offset:20992
	ds_read_b128 v[104:107], v206 offset:20992
	ds_read_b128 v[108:111], v207 offset:20992
	ds_read_b128 v[140:143], v245 offset:20992
	s_waitcnt lgkmcnt(11)
	v_sub_f32_e32 v81, v95, v177
	v_sub_f32_e32 v80, v94, v176
	v_sub_f32_e32 v79, v93, v175
	v_sub_f32_e32 v78, v92, v174
	s_waitcnt lgkmcnt(10)
	v_sub_f32_e32 v77, v91, v181
	v_sub_f32_e32 v76, v90, v180
	v_sub_f32_e32 v75, v89, v179
	v_sub_f32_e32 v74, v88, v178
	s_waitcnt lgkmcnt(9)
	v_sub_f32_e32 v73, v87, v251
	v_sub_f32_e32 v72, v86, v250
	v_sub_f32_e32 v71, v85, v249
	v_sub_f32_e32 v70, v84, v248
	s_waitcnt lgkmcnt(8)
	v_sub_f32_e32 v69, v83, v255
	v_sub_f32_e32 v68, v82, v254
	v_sub_f32_e32 v67, v33, v253
	v_sub_f32_e32 v66, v32, v252
	s_nop 1
	s_setprio 1
	s_waitcnt lgkmcnt(3)
	v_mfma_f32_32x32x16_bf16 v[66:81], v[10:13], v[120:123], v[66:81]
	v_exp_f32_e32 v14, v40
	v_exp_f32_e32 v15, v48
	s_waitcnt lgkmcnt(2)
	v_mfma_f32_32x32x16_bf16 v[66:81], v[104:107], v[112:115], v[66:81]
	ds_read_b64_tr_b16 v[10:11], v168 offset:3072
	ds_read_b64_tr_b16 v[12:13], v168 offset:4608
	ds_read_b64_tr_b16 v[104:105], v168 offset:3136
	ds_read_b64_tr_b16 v[106:107], v168 offset:4672
	v_mfma_f32_32x32x16_bf16 v[50:65], v[2:5], v[96:99], v[50:65]
	v_exp_f32_e32 v2, v34
	v_exp_f32_e32 v4, v35
	v_exp_f32_e32 v3, v42
	v_exp_f32_e32 v5, v43
	v_mfma_f32_32x32x16_bf16 v[16:31], v[6:9], v[96:99], v[16:31]
	v_exp_f32_e32 v6, v36
	v_exp_f32_e32 v8, v37
	v_exp_f32_e32 v7, v44
	v_exp_f32_e32 v9, v45
	s_waitcnt lgkmcnt(5)
	v_mfma_f32_32x32x16_bf16 v[66:81], v[108:111], v[116:119], v[66:81]
	s_waitcnt lgkmcnt(2)
	v_mfma_f32_32x32x16_bf16 v[50:65], v[10:13], v[100:103], v[50:65]
	v_exp_f32_e32 v10, v38
	v_exp_f32_e32 v12, v39
	v_exp_f32_e32 v11, v46
	v_exp_f32_e32 v13, v47
	s_waitcnt lgkmcnt(0)
	v_mfma_f32_32x32x16_bf16 v[16:31], v[104:107], v[100:103], v[16:31]
	v_exp_f32_e32 v102, v41
	v_exp_f32_e32 v103, v49
	v_add_f32_e32 v1, v14, v15
	v_add_f32_e32 v1, v1, v2
	v_add_f32_e32 v1, v1, v4
	v_add_f32_e32 v1, v1, v3
	v_add_f32_e32 v1, v1, v5
	v_add_f32_e32 v1, v1, v6
	v_add_f32_e32 v1, v1, v8
	v_add_f32_e32 v1, v1, v7
	v_add_f32_e32 v1, v1, v9
	v_add_f32_e32 v1, v1, v10
	v_add_f32_e32 v1, v1, v12
	v_add_f32_e32 v1, v1, v11
	v_add_f32_e32 v1, v1, v13
	v_add_f32_e32 v1, v1, v102
	v_add_f32_e32 v1, v1, v103
	v_add_f32_e32 v160, v160, v1
	v_mfma_f32_32x32x16_bf16 v[66:81], v[140:143], v[124:127], v[66:81]
	v_cvt_pk_bf16_f32 v98, v10, v12
	v_cvt_pk_bf16_f32 v96, v2, v4
	v_cvt_pk_bf16_f32 v97, v6, v8
	v_cvt_pk_bf16_f32 v99, v14, v102
	v_cvt_pk_bf16_f32 v100, v3, v5
	v_cvt_pk_bf16_f32 v101, v7, v9
	v_cvt_pk_bf16_f32 v102, v11, v13
	v_cvt_pk_bf16_f32 v103, v15, v103
	s_setprio 0
	s_waitcnt vmcnt(0)
	ds_write_b128 v159, v[136:139] offset:41728
	s_and_saveexec_b64 s[16:17], s[6:7]
	s_cbranch_execz .LfB_734_0
	s_mov_b32 s90, 0x3fb8aa3b
	v_mul_f32_e32 v2, 0x3fb8aa3b, v128
	v_mul_f32_e32 v3, 0x3fb8aa3b, v129
	v_mul_f32_e32 v4, 0x3fb8aa3b, v130
	v_mul_f32_e32 v5, 0x3fb8aa3b, v131
	ds_write_b128 v158, v[2:5] offset:62208
.LfB_734_0:
	s_or_b64 exec, exec, s[16:17]
	ds_write_b128 v161, v[132:135] offset:28928
	s_add_i32 s82, s82, 2
	s_add_i32 s14, s14, 64
	s_add_i32 s83, s83, 1
	s_mov_b32 s12, 0x0
	s_mov_b32 s15, 0x5100
	s_mov_b32 s97, 0xa200
	s_mov_b32 s92, 0x0
	s_cmp_eq_u32 s93, s83
	s_waitcnt lgkmcnt(0)
	s_barrier
	s_cbranch_scc1 .LBB0_735
	s_add_i32 s12, s82, -1
	s_cmp_lt_i32 s12, s98
	s_cbranch_scc0 .LfB_generic
	s_add_i32 s12, s83, 0x202
	s_cmp_lt_i32 s12, s9
	s_cbranch_scc1 .LfB_iter1
	s_branch .LfB_generic

.LfB_688_1:
	s_or_b64 exec, exec, s[20:21]
	s_ashr_i32 s15, s14, 31
	s_lshl_b64 s[20:21], s[14:15], 13
	s_add_u32 s20, s95, s20
	s_addc_u32 s21, s96, s21
	s_add_u32 s20, s20, 0x1000
	s_addc_u32 s21, s21, 0
	global_load_dwordx4 v[132:135], v182, s[20:21] offset:2048
	s_waitcnt lgkmcnt(0)
	ds_read_b128 v[174:177], v148 offset:41696
	ds_read_b128 v[178:181], v148 offset:41664
	ds_read_b128 v[248:251], v148 offset:41632
	ds_read_b128 v[252:255], v148 offset:41600
	ds_read_b64_tr_b16 v[2:3], v167 offset:0
	ds_read_b64_tr_b16 v[4:5], v167 offset:1536
	ds_read_b64_tr_b16 v[8:9], v167 offset:1600
	ds_read_b64_tr_b16 v[6:7], v167 offset:64
	ds_read_b128 v[10:13], v183 offset:25088
	ds_read_b128 v[104:107], v206 offset:25088
	ds_read_b128 v[108:111], v207 offset:25088
	ds_read_b128 v[140:143], v245 offset:25088
	s_waitcnt lgkmcnt(11)
	v_sub_f32_e32 v49, v95, v177
	v_sub_f32_e32 v48, v94, v176
	v_sub_f32_e32 v47, v93, v175
	v_sub_f32_e32 v46, v92, v174
	s_waitcnt lgkmcnt(10)
	v_sub_f32_e32 v45, v91, v181
	v_sub_f32_e32 v44, v90, v180
	v_sub_f32_e32 v43, v89, v179
	v_sub_f32_e32 v42, v88, v178
	s_waitcnt lgkmcnt(9)
	v_sub_f32_e32 v41, v87, v251
	v_sub_f32_e32 v40, v86, v250
	v_sub_f32_e32 v39, v85, v249
	v_sub_f32_e32 v38, v84, v248
	s_waitcnt lgkmcnt(8)
	v_sub_f32_e32 v37, v83, v255
	v_sub_f32_e32 v36, v82, v254
	v_sub_f32_e32 v35, v33, v253
	v_sub_f32_e32 v34, v32, v252
	s_nop 1
	s_setprio 1
	s_waitcnt lgkmcnt(3)
	v_mfma_f32_32x32x16_bf16 v[34:49], v[10:13], v[120:123], v[34:49]
	v_exp_f32_e32 v14, v72
	v_exp_f32_e32 v15, v80
	s_waitcnt lgkmcnt(2)
	v_mfma_f32_32x32x16_bf16 v[34:49], v[104:107], v[112:115], v[34:49]
	ds_read_b64_tr_b16 v[10:11], v167 offset:3072
	ds_read_b64_tr_b16 v[12:13], v167 offset:4608
	ds_read_b64_tr_b16 v[104:105], v167 offset:3136
	ds_read_b64_tr_b16 v[106:107], v167 offset:4672
	v_mfma_f32_32x32x16_bf16 v[50:65], v[2:5], v[96:99], v[50:65]
	v_exp_f32_e32 v2, v66
	v_exp_f32_e32 v4, v67
	v_exp_f32_e32 v3, v74
	v_exp_f32_e32 v5, v75
	v_mfma_f32_32x32x16_bf16 v[16:31], v[6:9], v[96:99], v[16:31]
	v_exp_f32_e32 v6, v68
	v_exp_f32_e32 v8, v69
	v_exp_f32_e32 v7, v76
	v_exp_f32_e32 v9, v77
	s_waitcnt lgkmcnt(5)
	v_mfma_f32_32x32x16_bf16 v[34:49], v[108:111], v[116:119], v[34:49]
	s_waitcnt lgkmcnt(2)
	v_mfma_f32_32x32x16_bf16 v[50:65], v[10:13], v[100:103], v[50:65]
	v_exp_f32_e32 v10, v70
	v_exp_f32_e32 v12, v71
	v_exp_f32_e32 v11, v78
	v_exp_f32_e32 v13, v79
	s_waitcnt lgkmcnt(0)
	v_mfma_f32_32x32x16_bf16 v[16:31], v[104:107], v[100:103], v[16:31]
	v_exp_f32_e32 v102, v73
	v_exp_f32_e32 v103, v81
	v_add_f32_e32 v1, v14, v15
	v_add_f32_e32 v1, v1, v2
	v_add_f32_e32 v1, v1, v4
	v_add_f32_e32 v1, v1, v3
	v_add_f32_e32 v1, v1, v5
	v_add_f32_e32 v1, v1, v6
	v_add_f32_e32 v1, v1, v8
	v_add_f32_e32 v1, v1, v7
	v_add_f32_e32 v1, v1, v9
	v_add_f32_e32 v1, v1, v10
	v_add_f32_e32 v1, v1, v12
	v_add_f32_e32 v1, v1, v11
	v_add_f32_e32 v1, v1, v13
	v_add_f32_e32 v1, v1, v102
	v_add_f32_e32 v1, v1, v103
	v_add_f32_e32 v160, v160, v1
	v_mfma_f32_32x32x16_bf16 v[34:49], v[140:143], v[124:127], v[34:49]
	v_cvt_pk_bf16_f32 v98, v10, v12
	v_cvt_pk_bf16_f32 v96, v2, v4
	v_cvt_pk_bf16_f32 v97, v6, v8
	v_cvt_pk_bf16_f32 v99, v14, v102
	v_cvt_pk_bf16_f32 v100, v3, v5
	v_cvt_pk_bf16_f32 v101, v7, v9
	v_cvt_pk_bf16_f32 v102, v11, v13
	v_cvt_pk_bf16_f32 v103, v15, v103
	s_setprio 0
	s_waitcnt lgkmcnt(0)
	ds_read_b128 v[174:177], v148 offset:62304
	ds_read_b128 v[178:181], v148 offset:62272
	ds_read_b128 v[248:251], v148 offset:62240
	ds_read_b128 v[252:255], v148 offset:62208
	ds_read_b64_tr_b16 v[2:3], v168 offset:20736
	ds_read_b64_tr_b16 v[4:5], v168 offset:22272
	ds_read_b64_tr_b16 v[8:9], v168 offset:22336
	ds_read_b64_tr_b16 v[6:7], v168 offset:20800
	ds_read_b128 v[10:13], v183 offset:41728
	ds_read_b128 v[104:107], v206 offset:41728
	ds_read_b128 v[108:111], v207 offset:41728
	ds_read_b128 v[140:143], v245 offset:41728
	s_waitcnt lgkmcnt(11)
	v_sub_f32_e32 v81, v95, v177
	v_sub_f32_e32 v80, v94, v176
	v_sub_f32_e32 v79, v93, v175
	v_sub_f32_e32 v78, v92, v174
	s_waitcnt lgkmcnt(10)
	v_sub_f32_e32 v77, v91, v181
	v_sub_f32_e32 v76, v90, v180
	v_sub_f32_e32 v75, v89, v179
	v_sub_f32_e32 v74, v88, v178
	s_waitcnt lgkmcnt(9)
	v_sub_f32_e32 v73, v87, v251
	v_sub_f32_e32 v72, v86, v250
	v_sub_f32_e32 v71, v85, v249
	v_sub_f32_e32 v70, v84, v248
	s_waitcnt lgkmcnt(8)
	v_sub_f32_e32 v69, v83, v255
	v_sub_f32_e32 v68, v82, v254
	v_sub_f32_e32 v67, v33, v253
	v_sub_f32_e32 v66, v32, v252
	s_nop 1
	s_setprio 1
	s_waitcnt lgkmcnt(3)
	v_mfma_f32_32x32x16_bf16 v[66:81], v[10:13], v[120:123], v[66:81]
	v_exp_f32_e32 v14, v40
	v_exp_f32_e32 v15, v48
	s_waitcnt lgkmcnt(2)
	v_mfma_f32_32x32x16_bf16 v[66:81], v[104:107], v[112:115], v[66:81]
	ds_read_b64_tr_b16 v[10:11], v168 offset:23808
	ds_read_b64_tr_b16 v[12:13], v168 offset:25344
	ds_read_b64_tr_b16 v[104:105], v168 offset:23872
	ds_read_b64_tr_b16 v[106:107], v168 offset:25408
	v_mfma_f32_32x32x16_bf16 v[50:65], v[2:5], v[96:99], v[50:65]
	v_exp_f32_e32 v2, v34
	v_exp_f32_e32 v4, v35
	v_exp_f32_e32 v3, v42
	v_exp_f32_e32 v5, v43
	v_mfma_f32_32x32x16_bf16 v[16:31], v[6:9], v[96:99], v[16:31]
	v_exp_f32_e32 v6, v36
	v_exp_f32_e32 v8, v37
	v_exp_f32_e32 v7, v44
	v_exp_f32_e32 v9, v45
	s_waitcnt lgkmcnt(5)
	v_mfma_f32_32x32x16_bf16 v[66:81], v[108:111], v[116:119], v[66:81]
	s_waitcnt lgkmcnt(2)
	v_mfma_f32_32x32x16_bf16 v[50:65], v[10:13], v[100:103], v[50:65]
	v_exp_f32_e32 v10, v38
	v_exp_f32_e32 v12, v39
	v_exp_f32_e32 v11, v46
	v_exp_f32_e32 v13, v47
	s_waitcnt lgkmcnt(0)
	v_mfma_f32_32x32x16_bf16 v[16:31], v[104:107], v[100:103], v[16:31]
	v_exp_f32_e32 v102, v41
	v_exp_f32_e32 v103, v49
	v_add_f32_e32 v1, v14, v15
	v_add_f32_e32 v1, v1, v2
	v_add_f32_e32 v1, v1, v4
	v_add_f32_e32 v1, v1, v3
	v_add_f32_e32 v1, v1, v5
	v_add_f32_e32 v1, v1, v6
	v_add_f32_e32 v1, v1, v8
	v_add_f32_e32 v1, v1, v7
	v_add_f32_e32 v1, v1, v9
	v_add_f32_e32 v1, v1, v10
	v_add_f32_e32 v1, v1, v12
	v_add_f32_e32 v1, v1, v11
	v_add_f32_e32 v1, v1, v13
	v_add_f32_e32 v1, v1, v102
	v_add_f32_e32 v1, v1, v103
	v_add_f32_e32 v160, v160, v1
	v_mfma_f32_32x32x16_bf16 v[66:81], v[140:143], v[124:127], v[66:81]
	v_cvt_pk_bf16_f32 v98, v10, v12
	v_cvt_pk_bf16_f32 v96, v2, v4
	v_cvt_pk_bf16_f32 v97, v6, v8
	v_cvt_pk_bf16_f32 v99, v14, v102
	v_cvt_pk_bf16_f32 v100, v3, v5
	v_cvt_pk_bf16_f32 v101, v7, v9
	v_cvt_pk_bf16_f32 v102, v11, v13
	v_cvt_pk_bf16_f32 v103, v15, v103
	s_setprio 0
	s_waitcnt vmcnt(0)
	ds_write_b128 v159, v[136:139] offset:256
	s_and_saveexec_b64 s[16:17], s[6:7]
	s_cbranch_execz .LfB_734_1
	s_mov_b32 s90, 0x3fb8aa3b
	v_mul_f32_e32 v2, 0x3fb8aa3b, v128
	v_mul_f32_e32 v3, 0x3fb8aa3b, v129
	v_mul_f32_e32 v4, 0x3fb8aa3b, v130
	v_mul_f32_e32 v5, 0x3fb8aa3b, v131
	ds_write_b128 v158, v[2:5] offset:20736
.LfB_734_1:
	s_or_b64 exec, exec, s[16:17]
	ds_write_b128 v161, v[132:135] offset:49664
	s_add_i32 s82, s82, 2
	s_add_i32 s14, s14, 64
	s_add_i32 s83, s83, 1
	s_mov_b32 s12, 0x5100
	s_mov_b32 s15, 0xa200
	s_mov_b32 s97, 0x0
	s_mov_b32 s92, 0x5100
	s_cmp_eq_u32 s93, s83
	s_waitcnt lgkmcnt(0)
	s_barrier
	s_cbranch_scc1 .LBB0_735
	s_add_i32 s12, s82, -1
	s_cmp_lt_i32 s12, s98
	s_cbranch_scc0 .LfB_generic
	s_add_i32 s12, s83, 0x202
	s_cmp_lt_i32 s12, s9
	s_cbranch_scc1 .LfB_iter2
	s_branch .LfB_generic

.LfB_688_2:
	s_or_b64 exec, exec, s[20:21]
	s_ashr_i32 s15, s14, 31
	s_lshl_b64 s[20:21], s[14:15], 13
	s_add_u32 s20, s95, s20
	s_addc_u32 s21, s96, s21
	s_add_u32 s20, s20, 0x1000
	s_addc_u32 s21, s21, 0
	global_load_dwordx4 v[132:135], v182, s[20:21] offset:2048
	s_waitcnt lgkmcnt(0)
	ds_read_b128 v[174:177], v148 offset:62432
	ds_read_b128 v[178:181], v148 offset:62400
	ds_read_b128 v[248:251], v148 offset:62368
	ds_read_b128 v[252:255], v148 offset:62336
	ds_read_b64_tr_b16 v[2:3], v167 offset:20736
	ds_read_b64_tr_b16 v[4:5], v167 offset:22272
	ds_read_b64_tr_b16 v[8:9], v167 offset:22336
	ds_read_b64_tr_b16 v[6:7], v167 offset:20800
	ds_read_b128 v[10:13], v183 offset:45824
	ds_read_b128 v[104:107], v206 offset:45824
	ds_read_b128 v[108:111], v207 offset:45824
	ds_read_b128 v[140:143], v245 offset:45824
	s_waitcnt lgkmcnt(11)
	v_sub_f32_e32 v49, v95, v177
	v_sub_f32_e32 v48, v94, v176
	v_sub_f32_e32 v47, v93, v175
	v_sub_f32_e32 v46, v92, v174
	s_waitcnt lgkmcnt(10)
	v_sub_f32_e32 v45, v91, v181
	v_sub_f32_e32 v44, v90, v180
	v_sub_f32_e32 v43, v89, v179
	v_sub_f32_e32 v42, v88, v178
	s_waitcnt lgkmcnt(9)
	v_sub_f32_e32 v41, v87, v251
	v_sub_f32_e32 v40, v86, v250
	v_sub_f32_e32 v39, v85, v249
	v_sub_f32_e32 v38, v84, v248
	s_waitcnt lgkmcnt(8)
	v_sub_f32_e32 v37, v83, v255
	v_sub_f32_e32 v36, v82, v254
	v_sub_f32_e32 v35, v33, v253
	v_sub_f32_e32 v34, v32, v252
	s_nop 1
	s_setprio 1
	s_waitcnt lgkmcnt(3)
	v_mfma_f32_32x32x16_bf16 v[34:49], v[10:13], v[120:123], v[34:49]
	v_exp_f32_e32 v14, v72
	v_exp_f32_e32 v15, v80
	s_waitcnt lgkmcnt(2)
	v_mfma_f32_32x32x16_bf16 v[34:49], v[104:107], v[112:115], v[34:49]
	ds_read_b64_tr_b16 v[10:11], v167 offset:23808
	ds_read_b64_tr_b16 v[12:13], v167 offset:25344
	ds_read_b64_tr_b16 v[104:105], v167 offset:23872
	ds_read_b64_tr_b16 v[106:107], v167 offset:25408
	v_mfma_f32_32x32x16_bf16 v[50:65], v[2:5], v[96:99], v[50:65]
	v_exp_f32_e32 v2, v66
	v_exp_f32_e32 v4, v67
	v_exp_f32_e32 v3, v74
	v_exp_f32_e32 v5, v75
	v_mfma_f32_32x32x16_bf16 v[16:31], v[6:9], v[96:99], v[16:31]
	v_exp_f32_e32 v6, v68
	v_exp_f32_e32 v8, v69
	v_exp_f32_e32 v7, v76
	v_exp_f32_e32 v9, v77
	s_waitcnt lgkmcnt(5)
	v_mfma_f32_32x32x16_bf16 v[34:49], v[108:111], v[116:119], v[34:49]
	s_waitcnt lgkmcnt(2)
	v_mfma_f32_32x32x16_bf16 v[50:65], v[10:13], v[100:103], v[50:65]
	v_exp_f32_e32 v10, v70
	v_exp_f32_e32 v12, v71
	v_exp_f32_e32 v11, v78
	v_exp_f32_e32 v13, v79
	s_waitcnt lgkmcnt(0)
	v_mfma_f32_32x32x16_bf16 v[16:31], v[104:107], v[100:103], v[16:31]
	v_exp_f32_e32 v102, v73
	v_exp_f32_e32 v103, v81
	v_add_f32_e32 v1, v14, v15
	v_add_f32_e32 v1, v1, v2
	v_add_f32_e32 v1, v1, v4
	v_add_f32_e32 v1, v1, v3
	v_add_f32_e32 v1, v1, v5
	v_add_f32_e32 v1, v1, v6
	v_add_f32_e32 v1, v1, v8
	v_add_f32_e32 v1, v1, v7
	v_add_f32_e32 v1, v1, v9
	v_add_f32_e32 v1, v1, v10
	v_add_f32_e32 v1, v1, v12
	v_add_f32_e32 v1, v1, v11
	v_add_f32_e32 v1, v1, v13
	v_add_f32_e32 v1, v1, v102
	v_add_f32_e32 v1, v1, v103
	v_add_f32_e32 v160, v160, v1
	v_mfma_f32_32x32x16_bf16 v[34:49], v[140:143], v[124:127], v[34:49]
	v_cvt_pk_bf16_f32 v98, v10, v12
	v_cvt_pk_bf16_f32 v96, v2, v4
	v_cvt_pk_bf16_f32 v97, v6, v8
	v_cvt_pk_bf16_f32 v99, v14, v102
	v_cvt_pk_bf16_f32 v100, v3, v5
	v_cvt_pk_bf16_f32 v101, v7, v9
	v_cvt_pk_bf16_f32 v102, v11, v13
	v_cvt_pk_bf16_f32 v103, v15, v103
	s_setprio 0
	s_waitcnt lgkmcnt(0)
	ds_read_b128 v[174:177], v148 offset:20832
	ds_read_b128 v[178:181], v148 offset:20800
	ds_read_b128 v[248:251], v148 offset:20768
	ds_read_b128 v[252:255], v148 offset:20736
	ds_read_b64_tr_b16 v[2:3], v168 offset:41472
	ds_read_b64_tr_b16 v[4:5], v168 offset:43008
	ds_read_b64_tr_b16 v[8:9], v168 offset:43072
	ds_read_b64_tr_b16 v[6:7], v168 offset:41536
	ds_read_b128 v[10:13], v183 offset:256
	ds_read_b128 v[104:107], v206 offset:256
	ds_read_b128 v[108:111], v207 offset:256
	ds_read_b128 v[140:143], v245 offset:256
	s_waitcnt lgkmcnt(11)
	v_sub_f32_e32 v81, v95, v177
	v_sub_f32_e32 v80, v94, v176
	v_sub_f32_e32 v79, v93, v175
	v_sub_f32_e32 v78, v92, v174
	s_waitcnt lgkmcnt(10)
	v_sub_f32_e32 v77, v91, v181
	v_sub_f32_e32 v76, v90, v180
	v_sub_f32_e32 v75, v89, v179
	v_sub_f32_e32 v74, v88, v178
	s_waitcnt lgkmcnt(9)
	v_sub_f32_e32 v73, v87, v251
	v_sub_f32_e32 v72, v86, v250
	v_sub_f32_e32 v71, v85, v249
	v_sub_f32_e32 v70, v84, v248
	s_waitcnt lgkmcnt(8)
	v_sub_f32_e32 v69, v83, v255
	v_sub_f32_e32 v68, v82, v254
	v_sub_f32_e32 v67, v33, v253
	v_sub_f32_e32 v66, v32, v252
	s_nop 1
	s_setprio 1
	s_waitcnt lgkmcnt(3)
	v_mfma_f32_32x32x16_bf16 v[66:81], v[10:13], v[120:123], v[66:81]
	v_exp_f32_e32 v14, v40
	v_exp_f32_e32 v15, v48
	s_waitcnt lgkmcnt(2)
	v_mfma_f32_32x32x16_bf16 v[66:81], v[104:107], v[112:115], v[66:81]
	ds_read_b64_tr_b16 v[10:11], v168 offset:44544
	ds_read_b64_tr_b16 v[12:13], v168 offset:46080
	ds_read_b64_tr_b16 v[104:105], v168 offset:44608
	ds_read_b64_tr_b16 v[106:107], v168 offset:46144
	v_mfma_f32_32x32x16_bf16 v[50:65], v[2:5], v[96:99], v[50:65]
	v_exp_f32_e32 v2, v34
	v_exp_f32_e32 v4, v35
	v_exp_f32_e32 v3, v42
	v_exp_f32_e32 v5, v43
	v_mfma_f32_32x32x16_bf16 v[16:31], v[6:9], v[96:99], v[16:31]
	v_exp_f32_e32 v6, v36
	v_exp_f32_e32 v8, v37
	v_exp_f32_e32 v7, v44
	v_exp_f32_e32 v9, v45
	s_waitcnt lgkmcnt(5)
	v_mfma_f32_32x32x16_bf16 v[66:81], v[108:111], v[116:119], v[66:81]
	s_waitcnt lgkmcnt(2)
	v_mfma_f32_32x32x16_bf16 v[50:65], v[10:13], v[100:103], v[50:65]
	v_exp_f32_e32 v10, v38
	v_exp_f32_e32 v12, v39
	v_exp_f32_e32 v11, v46
	v_exp_f32_e32 v13, v47
	s_waitcnt lgkmcnt(0)
	v_mfma_f32_32x32x16_bf16 v[16:31], v[104:107], v[100:103], v[16:31]
	v_exp_f32_e32 v102, v41
	v_exp_f32_e32 v103, v49
	v_add_f32_e32 v1, v14, v15
	v_add_f32_e32 v1, v1, v2
	v_add_f32_e32 v1, v1, v4
	v_add_f32_e32 v1, v1, v3
	v_add_f32_e32 v1, v1, v5
	v_add_f32_e32 v1, v1, v6
	v_add_f32_e32 v1, v1, v8
	v_add_f32_e32 v1, v1, v7
	v_add_f32_e32 v1, v1, v9
	v_add_f32_e32 v1, v1, v10
	v_add_f32_e32 v1, v1, v12
	v_add_f32_e32 v1, v1, v11
	v_add_f32_e32 v1, v1, v13
	v_add_f32_e32 v1, v1, v102
	v_add_f32_e32 v1, v1, v103
	v_add_f32_e32 v160, v160, v1
	v_mfma_f32_32x32x16_bf16 v[66:81], v[140:143], v[124:127], v[66:81]
	v_cvt_pk_bf16_f32 v98, v10, v12
	v_cvt_pk_bf16_f32 v96, v2, v4
	v_cvt_pk_bf16_f32 v97, v6, v8
	v_cvt_pk_bf16_f32 v99, v14, v102
	v_cvt_pk_bf16_f32 v100, v3, v5
	v_cvt_pk_bf16_f32 v101, v7, v9
	v_cvt_pk_bf16_f32 v102, v11, v13
	v_cvt_pk_bf16_f32 v103, v15, v103
	s_setprio 0
	s_waitcnt vmcnt(0)
	ds_write_b128 v159, v[136:139] offset:20992
	s_and_saveexec_b64 s[16:17], s[6:7]
	s_cbranch_execz .LfB_734_2
	s_mov_b32 s90, 0x3fb8aa3b
	v_mul_f32_e32 v2, 0x3fb8aa3b, v128
	v_mul_f32_e32 v3, 0x3fb8aa3b, v129
	v_mul_f32_e32 v4, 0x3fb8aa3b, v130
	v_mul_f32_e32 v5, 0x3fb8aa3b, v131
	ds_write_b128 v158, v[2:5] offset:41472
.LfB_734_2:
	s_or_b64 exec, exec, s[16:17]
	ds_write_b128 v161, v[132:135] offset:8192
	s_add_i32 s82, s82, 2
	s_add_i32 s14, s14, 64
	s_add_i32 s83, s83, 1
	s_mov_b32 s12, 0xa200
	s_mov_b32 s15, 0x0
	s_mov_b32 s97, 0x5100
	s_mov_b32 s92, 0xa200
	s_cmp_eq_u32 s93, s83
	s_waitcnt lgkmcnt(0)
	s_barrier
	s_cbranch_scc1 .LBB0_735
	s_add_i32 s12, s82, -1
	s_cmp_lt_i32 s12, s98
	s_cbranch_scc0 .LfB_generic
	s_add_i32 s12, s83, 0x202
	s_cmp_lt_i32 s12, s9
	s_cbranch_scc1 .LfB_iter0
	s_branch .LfB_generic
